# v34 plus: in the same-XCD group barrier the L1 invalidate is issued together with the arrival atomic (overlapping the poll) instead of after the poll; all waves are parked at the workgroup barrier mea
# baseline (speedup 1.0000x reference)
.LBB0_1098:
	v_readlane_b32 s2, v255, 39
	s_nop 1
	v_mov_b32_e32 v0, s2
	ds_read_b32 v0, v0
	s_waitcnt lgkmcnt(0)
	v_cmp_eq_u32_e32 vcc, 0, v0
	s_or_b64 s[0:1], s[0:1], vcc
	s_andn2_b64 vcc, exec, s[0:1]
	s_mov_b64 s[0:1], -1
	s_cbranch_vccz .LBB0_1116
	s_waitcnt vmcnt(0)
	s_waitcnt vmcnt(0)
	s_barrier
	s_mov_b64 s[0:1], exec
	v_readlane_b32 s2, v254, 6
	v_readlane_b32 s3, v254, 7
	s_and_b64 s[2:3], s[0:1], s[2:3]
	s_mov_b64 exec, s[2:3]
	s_cbranch_execz .LBB0_1115
	s_mov_b64 s[4:5], exec
	v_mbcnt_lo_u32_b32 v0, s4, 0
	v_mbcnt_hi_u32_b32 v0, s5, v0
	v_cmp_eq_u32_e32 vcc, 0, v0
	s_and_saveexec_b64 s[2:3], vcc
	s_cbranch_execz .LBB0_1102
	s_bcnt1_i32_b64 s4, s[4:5]
	v_mov_b32_e32 v1, s4
	global_atomic_add v1, v177, v1, s[94:95] sc0
	buffer_inv sc1

.LBB0_1108:
	global_load_dword v1, v177, s[94:95] sc1
	s_or_b64 s[4:5], s[4:5], exec
	s_waitcnt vmcnt(0)
	v_cmp_lt_u32_e32 vcc, v1, v0
	s_and_saveexec_b64 s[6:7], vcc
	s_cbranch_execz .LBB0_1107
	s_sleep 1
	global_load_dword v1, v177, s[94:95] sc1
	s_mov_b64 s[10:11], -1
	s_waitcnt vmcnt(0)
	v_cmp_lt_u32_e32 vcc, v1, v0
	s_and_saveexec_b64 s[8:9], vcc
	s_cbranch_execz .LBB0_1106
	s_sleep 1
	global_load_dword v1, v177, s[94:95] sc1
	s_mov_b64 s[12:13], -1
	s_waitcnt vmcnt(0)
	v_cmp_lt_u32_e32 vcc, v1, v0
	s_and_saveexec_b64 s[10:11], vcc
	s_cbranch_execz .LBB0_1105
	s_sleep 1
	global_load_dword v1, v177, s[94:95] sc1
	s_mov_b64 s[14:15], -1
	s_waitcnt vmcnt(0)
	v_cmp_lt_u32_e32 vcc, v1, v0
	s_and_saveexec_b64 s[12:13], vcc
	s_cbranch_execz .LBB0_1104
	s_sleep 1
	global_load_dword v1, v177, s[94:95] sc1
	s_waitcnt vmcnt(0)
	v_cmp_lt_u32_e32 vcc, v1, v0
	s_and_saveexec_b64 s[16:17], vcc
	s_cbranch_execz .LBB0_1103
	s_add_i32 s18, s18, -5
	s_cmp_eq_u32 s18, 0
	s_cselect_b64 s[14:15], -1, 0
	s_orn2_b64 s[14:15], s[14:15], exec
	s_sleep 1
	s_branch .LBB0_1103
.LBB0_1114:
	s_or_b64 exec, exec, s[2:3]
	s_waitcnt vmcnt(0)
.LBB0_1115:
	s_or_b64 exec, exec, s[0:1]
	s_mov_b64 s[0:1], 0
	s_barrier
